# attention: second-generation fast path for unmasked tiles - key-half-major QK, per-key-half online softmax hidden in QK/PV MFMA gaps, deferred O rescale
# baseline (speedup 1.0000x reference)
.LaF1_fast:
	s_add_i32 s54, s52, 63
	s_cmp_le_i32 s54, s47
	s_cbranch_scc1 .LaG1_fast
	s_waitcnt vmcnt(0)
	s_bitcmp1_b32 s51, 0
	s_cselect_b32 s53, 0, 0xac00
	s_setprio 1
	v_add_u32_e32 v253, s53, v171
	v_add_u32_e32 v252, s53, v181
	ds_read_b128 v[196:199], v253
	ds_read_b128 v[200:203], v253 offset:12800
	ds_read_b128 v[204:207], v253 offset:32
	ds_read_b128 v[208:211], v253 offset:12832
	ds_read_b128 v[212:215], v253 offset:64
	ds_read_b128 v[216:219], v253 offset:12864
	s_waitcnt lgkmcnt(5)
	v_mfma_f32_32x32x16_bf16 v[66:81], v[196:199], v[110:113], 0
	ds_read_b128 v[220:223], v253 offset:96
	v_lshl_add_u64 v[244:245], s[2:3], 0, v[176:177]
	s_waitcnt lgkmcnt(5)
	v_mfma_f32_32x32x16_bf16 v[82:97], v[200:203], v[110:113], 0
	ds_read_b128 v[224:227], v253 offset:12896
	v_add_co_u32_e32 v246, vcc, 0x16020000, v244
	s_waitcnt lgkmcnt(5)
	v_mfma_f32_32x32x16_bf16 v[66:81], v[204:207], v[118:121], v[66:81]
	ds_read_b128 v[228:231], v253 offset:128
	s_nop 1
	s_waitcnt lgkmcnt(5)
	v_mfma_f32_32x32x16_bf16 v[82:97], v[208:211], v[118:121], v[82:97]
	ds_read_b128 v[232:235], v253 offset:12928
	v_addc_co_u32_e32 v247, vcc, 0, v245, vcc
	s_waitcnt lgkmcnt(5)
	v_mfma_f32_32x32x16_bf16 v[66:81], v[212:215], v[122:125], v[66:81]
	ds_read_b128 v[236:239], v253 offset:160
	v_add_co_u32_e32 v244, vcc, 0x16030000, v244
	s_waitcnt lgkmcnt(5)
	v_mfma_f32_32x32x16_bf16 v[82:97], v[216:219], v[122:125], v[82:97]
	ds_read_b128 v[240:243], v253 offset:12960
	s_nop 1
	s_waitcnt lgkmcnt(5)
	v_mfma_f32_32x32x16_bf16 v[66:81], v[220:223], v[126:129], v[66:81]
	ds_read_b128 v[196:199], v253 offset:192
	v_addc_co_u32_e32 v245, vcc, 0, v245, vcc
	s_waitcnt lgkmcnt(5)
	v_mfma_f32_32x32x16_bf16 v[82:97], v[224:227], v[126:129], v[82:97]
	ds_read_b128 v[200:203], v253 offset:12992
	global_load_dwordx4 v[98:101], v[246:247], off
	s_waitcnt lgkmcnt(5)
	v_mfma_f32_32x32x16_bf16 v[66:81], v[228:231], v[130:133], v[66:81]
	ds_read_b128 v[204:207], v253 offset:224
	global_load_dwordx4 v[102:105], v[244:245], off
	s_waitcnt lgkmcnt(5)
	v_mfma_f32_32x32x16_bf16 v[82:97], v[232:235], v[130:133], v[82:97]
	ds_read_b128 v[208:211], v253 offset:13024
	v_lshl_add_u64 v[246:247], s[2:3], 0, v[178:179]
	s_waitcnt lgkmcnt(5)
	v_mfma_f32_32x32x16_bf16 v[66:81], v[236:239], v[134:137], v[66:81]
	ds_read_b128 v[212:215], v253 offset:256
	v_add_co_u32_e32 v248, vcc, 0x1a000000, v246
	s_waitcnt lgkmcnt(5)
	v_mfma_f32_32x32x16_bf16 v[82:97], v[240:243], v[134:137], v[82:97]
	ds_read_b128 v[216:219], v253 offset:13056
	v_lshl_add_u64 v[244:245], s[2:3], 0, v[174:175]
	s_waitcnt lgkmcnt(5)
	v_mfma_f32_32x32x16_bf16 v[66:81], v[196:199], v[138:141], v[66:81]
	ds_read_b128 v[220:223], v253 offset:288
	s_nop 0
	s_waitcnt lgkmcnt(5)
	v_mfma_f32_32x32x16_bf16 v[82:97], v[200:203], v[138:141], v[82:97]
	ds_read_b128 v[224:227], v253 offset:13088
	v_addc_co_u32_e32 v249, vcc, 0, v247, vcc
	s_waitcnt lgkmcnt(5)
	v_mfma_f32_32x32x16_bf16 v[66:81], v[204:207], v[142:145], v[66:81]
	ds_read_b128 v[228:231], v253 offset:320
	global_load_dwordx4 v[106:109], v[244:245], off
	s_waitcnt lgkmcnt(5)
	v_mfma_f32_32x32x16_bf16 v[82:97], v[208:211], v[142:145], v[82:97]
	ds_read_b128 v[232:235], v253 offset:13120
	global_load_dwordx4 v[114:117], v[248:249], off offset:128
	s_waitcnt lgkmcnt(5)
	v_mfma_f32_32x32x16_bf16 v[66:81], v[212:215], v[150:153], v[66:81]
	ds_read_b128 v[236:239], v253 offset:352
	v_add_co_u32_e32 v244, vcc, 0x1a400000, v246
	s_waitcnt lgkmcnt(5)
	v_mfma_f32_32x32x16_bf16 v[82:97], v[216:219], v[150:153], v[82:97]
	ds_read_b128 v[240:243], v253 offset:13152
	s_nop 1
	s_waitcnt lgkmcnt(5)
	v_mfma_f32_32x32x16_bf16 v[66:81], v[220:223], v[154:157], v[66:81]
	v_addc_co_u32_e32 v245, vcc, 0, v247, vcc
	s_waitcnt lgkmcnt(4)
	v_mfma_f32_32x32x16_bf16 v[82:97], v[224:227], v[154:157], v[82:97]
	global_load_dwordx4 v[146:149], v[244:245], off offset:128
	s_waitcnt lgkmcnt(3)
	v_mfma_f32_32x32x16_bf16 v[66:81], v[228:231], v[158:161], v[66:81]
	s_waitcnt lgkmcnt(2)
	v_mfma_f32_32x32x16_bf16 v[82:97], v[232:235], v[158:161], v[82:97]
	s_waitcnt lgkmcnt(1)
	v_mfma_f32_32x32x16_bf16 v[66:81], v[236:239], v[162:165], v[66:81]
	s_waitcnt lgkmcnt(0)
	v_mfma_f32_32x32x16_bf16 v[82:97], v[240:243], v[162:165], v[82:97]
	ds_read_b128 v[196:199], v252 offset:25600
	ds_read_b128 v[200:203], v252 offset:30208
	ds_read_b128 v[204:207], v252 offset:34816
	ds_read_b128 v[208:211], v252 offset:39424
	ds_read_b128 v[212:215], v252 offset:25632
	ds_read_b128 v[216:219], v252 offset:30240
	s_setprio 0
	s_add_i32 s54, s52, 63
	s_cmp_le_i32 s54, s47
	s_cbranch_scc1 .LaF1_1
	v_add_u32_e32 v0, s52, v168
	v_add_u32_e32 v184, 32, v0
	v_cmp_le_i32_e32 vcc, v184, v173
	v_add_u32_e32 v184, 33, v0
	s_nop 3
	v_cndmask_b32_e32 v82, v180, v82, vcc
	v_cmp_lt_i32_e32 vcc, v0, v173
	s_nop 1
	v_cndmask_b32_e32 v67, v180, v67, vcc
	v_cmp_le_i32_e32 vcc, v0, v173
	s_nop 1
	v_cndmask_b32_e32 v66, v180, v66, vcc
	v_cmp_le_i32_e32 vcc, v184, v173
	v_add_u32_e32 v184, 2, v0
	s_nop 0
	v_cndmask_b32_e32 v83, v180, v83, vcc
	v_cmp_le_i32_e32 vcc, v184, v173
	v_add_u32_e32 v184, 34, v0
	s_nop 0
	v_cndmask_b32_e32 v68, v180, v68, vcc
	v_cmp_le_i32_e32 vcc, v184, v173
	v_add_u32_e32 v184, 3, v0
	s_nop 0
	v_cndmask_b32_e32 v84, v180, v84, vcc
	v_cmp_le_i32_e32 vcc, v184, v173
	v_add_u32_e32 v184, 35, v0
	s_nop 0
	v_cndmask_b32_e32 v69, v180, v69, vcc
	v_cmp_le_i32_e32 vcc, v184, v173
	v_add_u32_e32 v184, 4, v0
	s_nop 0
	v_cndmask_b32_e32 v85, v180, v85, vcc
	v_cmp_le_i32_e32 vcc, v184, v173
	v_add_u32_e32 v184, 36, v0
	s_nop 0
	v_cndmask_b32_e32 v70, v180, v70, vcc
	v_cmp_le_i32_e32 vcc, v184, v173
	v_add_u32_e32 v184, 5, v0
	s_nop 0
	v_cndmask_b32_e32 v86, v180, v86, vcc
	v_cmp_le_i32_e32 vcc, v184, v173
	v_add_u32_e32 v184, 37, v0
	s_nop 0
	v_cndmask_b32_e32 v71, v180, v71, vcc
	v_cmp_le_i32_e32 vcc, v184, v173
	v_add_u32_e32 v184, 6, v0
	s_nop 0
	v_cndmask_b32_e32 v87, v180, v87, vcc
	v_cmp_le_i32_e32 vcc, v184, v173
	v_add_u32_e32 v184, 38, v0
	s_nop 0
	v_cndmask_b32_e32 v72, v180, v72, vcc
	v_cmp_le_i32_e32 vcc, v184, v173
	v_add_u32_e32 v184, 7, v0
	s_nop 0
	v_cndmask_b32_e32 v88, v180, v88, vcc
	v_cmp_le_i32_e32 vcc, v184, v173
	v_add_u32_e32 v184, 39, v0
	s_nop 0
	v_cndmask_b32_e32 v73, v180, v73, vcc
	v_cmp_le_i32_e32 vcc, v184, v173
	v_add_u32_e32 v184, 16, v0
	s_nop 0
	v_cndmask_b32_e32 v89, v180, v89, vcc
	v_cmp_le_i32_e32 vcc, v184, v173
	v_add_u32_e32 v184, 48, v0
	s_nop 0
	v_cndmask_b32_e32 v74, v180, v74, vcc
	v_cmp_le_i32_e32 vcc, v184, v173
	v_add_u32_e32 v184, 17, v0
	s_nop 0
	v_cndmask_b32_e32 v90, v180, v90, vcc
	v_cmp_le_i32_e32 vcc, v184, v173
	v_add_u32_e32 v184, 49, v0
	s_nop 0
	v_cndmask_b32_e32 v75, v180, v75, vcc
	v_cmp_le_i32_e32 vcc, v184, v173
	v_add_u32_e32 v184, 18, v0
	s_nop 0
	v_cndmask_b32_e32 v91, v180, v91, vcc
	v_cmp_le_i32_e32 vcc, v184, v173
	v_add_u32_e32 v184, 50, v0
	s_nop 0
	v_cndmask_b32_e32 v76, v180, v76, vcc
	v_cmp_le_i32_e32 vcc, v184, v173
	v_add_u32_e32 v184, 19, v0
	s_nop 0
	v_cndmask_b32_e32 v92, v180, v92, vcc
	v_cmp_le_i32_e32 vcc, v184, v173
	v_add_u32_e32 v184, 51, v0
	s_nop 0
	v_cndmask_b32_e32 v77, v180, v77, vcc
	v_cmp_le_i32_e32 vcc, v184, v173
	v_add_u32_e32 v184, 20, v0
	s_nop 0
	v_cndmask_b32_e32 v93, v180, v93, vcc
	v_cmp_le_i32_e32 vcc, v184, v173
	v_add_u32_e32 v184, 52, v0
	s_nop 0
	v_cndmask_b32_e32 v78, v180, v78, vcc
	v_cmp_le_i32_e32 vcc, v184, v173
	v_add_u32_e32 v184, 21, v0
	s_nop 0
	v_cndmask_b32_e32 v94, v180, v94, vcc
	v_cmp_le_i32_e32 vcc, v184, v173
	v_add_u32_e32 v184, 53, v0
	s_nop 0
	v_cndmask_b32_e32 v79, v180, v79, vcc
	v_cmp_le_i32_e32 vcc, v184, v173
	v_add_u32_e32 v184, 22, v0
	s_nop 0
	v_cndmask_b32_e32 v95, v180, v95, vcc
	v_cmp_le_i32_e32 vcc, v184, v173
	v_add_u32_e32 v184, 54, v0
	s_nop 0
	v_cndmask_b32_e32 v80, v180, v80, vcc
	v_cmp_le_i32_e32 vcc, v184, v173
	v_add_u32_e32 v184, 23, v0
	v_add_u32_e32 v0, 55, v0
	v_cndmask_b32_e32 v96, v180, v96, vcc
	v_cmp_le_i32_e32 vcc, v184, v173
	s_nop 1
	v_cndmask_b32_e32 v81, v180, v81, vcc
	v_cmp_le_i32_e32 vcc, v0, v173
	s_nop 1
	v_cndmask_b32_e32 v97, v180, v97, vcc

.LaG1_fast:
	s_waitcnt vmcnt(0)
	s_bitcmp1_b32 s51, 0
	s_cselect_b32 s53, 0, 0xac00
	s_mov_b32 s98, 0
	s_setprio 1
	v_add_u32_e32 v253, s53, v171
	v_add_u32_e32 v252, s53, v181
	ds_read_b128 v[196:199], v253
	ds_read_b128 v[200:203], v253 offset:32
	ds_read_b128 v[204:207], v253 offset:64
	ds_read_b128 v[208:211], v253 offset:96
	ds_read_b128 v[212:215], v253 offset:128
	ds_read_b128 v[216:219], v253 offset:160
	s_waitcnt lgkmcnt(5)
	v_mfma_f32_32x32x16_bf16 v[66:81], v[196:199], v[110:113], 0
	ds_read_b128 v[220:223], v253 offset:192
	v_lshl_add_u64 v[244:245], s[2:3], 0, v[176:177]
	v_add_co_u32_e32 v246, vcc, 0x16020000, v244
	s_waitcnt lgkmcnt(5)
	v_mfma_f32_32x32x16_bf16 v[66:81], v[200:203], v[118:121], v[66:81]
	ds_read_b128 v[224:227], v253 offset:224
	s_nop 1
	v_addc_co_u32_e32 v247, vcc, 0, v245, vcc
	s_waitcnt lgkmcnt(5)
	v_mfma_f32_32x32x16_bf16 v[66:81], v[204:207], v[122:125], v[66:81]
	ds_read_b128 v[228:231], v253 offset:256
	v_add_co_u32_e32 v244, vcc, 0x16030000, v244
	s_nop 1
	s_waitcnt lgkmcnt(5)
	v_mfma_f32_32x32x16_bf16 v[66:81], v[208:211], v[126:129], v[66:81]
	ds_read_b128 v[232:235], v253 offset:288
	v_addc_co_u32_e32 v245, vcc, 0, v245, vcc
	global_load_dwordx4 v[98:101], v[246:247], off
	s_waitcnt lgkmcnt(5)
	v_mfma_f32_32x32x16_bf16 v[66:81], v[212:215], v[130:133], v[66:81]
	ds_read_b128 v[236:239], v253 offset:320
	global_load_dwordx4 v[102:105], v[244:245], off
	v_lshl_add_u64 v[246:247], s[2:3], 0, v[178:179]
	s_waitcnt lgkmcnt(5)
	v_mfma_f32_32x32x16_bf16 v[66:81], v[216:219], v[134:137], v[66:81]
	ds_read_b128 v[240:243], v253 offset:352
	v_add_co_u32_e32 v248, vcc, 0x1a000000, v246
	v_lshl_add_u64 v[244:245], s[2:3], 0, v[174:175]
	s_waitcnt lgkmcnt(5)
	v_mfma_f32_32x32x16_bf16 v[66:81], v[220:223], v[138:141], v[66:81]
	ds_read_b128 v[196:199], v253 offset:12800
	s_nop 0
	v_addc_co_u32_e32 v249, vcc, 0, v247, vcc
	s_waitcnt lgkmcnt(5)
	v_mfma_f32_32x32x16_bf16 v[66:81], v[224:227], v[142:145], v[66:81]
	ds_read_b128 v[200:203], v253 offset:12832
	global_load_dwordx4 v[106:109], v[244:245], off
	global_load_dwordx4 v[114:117], v[248:249], off offset:128
	s_waitcnt lgkmcnt(5)
	v_mfma_f32_32x32x16_bf16 v[66:81], v[228:231], v[150:153], v[66:81]
	ds_read_b128 v[204:207], v253 offset:12864
	v_add_co_u32_e32 v244, vcc, 0x1a400000, v246
	s_nop 1
	s_waitcnt lgkmcnt(5)
	v_mfma_f32_32x32x16_bf16 v[66:81], v[232:235], v[154:157], v[66:81]
	ds_read_b128 v[208:211], v253 offset:12896
	v_addc_co_u32_e32 v245, vcc, 0, v247, vcc
	global_load_dwordx4 v[146:149], v[244:245], off offset:128
	s_waitcnt lgkmcnt(5)
	v_mfma_f32_32x32x16_bf16 v[66:81], v[236:239], v[158:161], v[66:81]
	ds_read_b128 v[212:215], v253 offset:12928
	s_waitcnt lgkmcnt(5)
	v_mfma_f32_32x32x16_bf16 v[66:81], v[240:243], v[162:165], v[66:81]
	ds_read_b128 v[216:219], v253 offset:12960
	s_waitcnt lgkmcnt(5)
	v_mfma_f32_32x32x16_bf16 v[82:97], v[196:199], v[110:113], 0
	ds_read_b128 v[220:223], v253 offset:12992
	s_waitcnt lgkmcnt(5)
	v_mfma_f32_32x32x16_bf16 v[82:97], v[200:203], v[118:121], v[82:97]
	ds_read_b128 v[224:227], v253 offset:13024
	s_waitcnt lgkmcnt(5)
	v_mfma_f32_32x32x16_bf16 v[82:97], v[204:207], v[122:125], v[82:97]
	ds_read_b128 v[228:231], v253 offset:13056
	v_max3_f32 v0, v66, v67, v68
	v_max3_f32 v184, v69, v70, v71
	v_max3_f32 v0, v0, v72, v73
	v_max3_f32 v184, v184, v74, v75
	v_max3_f32 v0, v0, v76, v77
	v_max3_f32 v184, v184, v78, v79
	v_max3_f32 v0, v0, v80, v81
	s_waitcnt lgkmcnt(5)
	v_mfma_f32_32x32x16_bf16 v[82:97], v[208:211], v[126:129], v[82:97]
	ds_read_b128 v[232:235], v253 offset:13088
	v_max_f32_e32 v0, v0, v184
	v_mov_b32_e32 v184, v0
	s_nop 1
	v_permlane32_swap_b32_e32 v0, v184
	v_max_f32_e32 v184, v184, v184
	v_max_f32_e32 v0, v0, v0
	v_max_f32_e32 v0, v0, v184
	s_waitcnt lgkmcnt(5)
	v_mfma_f32_32x32x16_bf16 v[82:97], v[212:215], v[130:133], v[82:97]
	ds_read_b128 v[236:239], v253 offset:13120
	v_sub_f32_e32 v184, v0, v183
	v_cmp_lt_f32_e32 vcc, s43, v184
	s_cbranch_vccnz .LaG1_R0
.LaG1_R0b:
	v_sub_f32_e32 v66, v66, v183
	v_sub_f32_e32 v67, v67, v183
	v_sub_f32_e32 v68, v68, v183
	s_waitcnt lgkmcnt(5)
	v_mfma_f32_32x32x16_bf16 v[82:97], v[216:219], v[134:137], v[82:97]
	ds_read_b128 v[240:243], v253 offset:13152
	v_sub_f32_e32 v69, v69, v183
	v_sub_f32_e32 v70, v70, v183
	v_sub_f32_e32 v71, v71, v183
	v_sub_f32_e32 v72, v72, v183
	v_sub_f32_e32 v73, v73, v183
	v_sub_f32_e32 v74, v74, v183
	v_sub_f32_e32 v75, v75, v183
	s_waitcnt lgkmcnt(5)
	v_mfma_f32_32x32x16_bf16 v[82:97], v[220:223], v[138:141], v[82:97]
	ds_read_b128 v[196:199], v252 offset:25600
	v_sub_f32_e32 v76, v76, v183
	v_sub_f32_e32 v77, v77, v183
	v_sub_f32_e32 v78, v78, v183
	v_sub_f32_e32 v79, v79, v183
	v_sub_f32_e32 v80, v80, v183
	v_sub_f32_e32 v81, v81, v183
	v_exp_f32_e32 v66, v66
	s_waitcnt lgkmcnt(5)
	v_mfma_f32_32x32x16_bf16 v[82:97], v[224:227], v[142:145], v[82:97]
	ds_read_b128 v[200:203], v252 offset:30208
	v_exp_f32_e32 v67, v67
	v_exp_f32_e32 v68, v68
	v_exp_f32_e32 v69, v69
	v_exp_f32_e32 v70, v70
	v_exp_f32_e32 v71, v71
	v_exp_f32_e32 v72, v72
	v_exp_f32_e32 v73, v73
	s_waitcnt lgkmcnt(5)
	v_mfma_f32_32x32x16_bf16 v[82:97], v[228:231], v[150:153], v[82:97]
	ds_read_b128 v[204:207], v252 offset:34816
	v_exp_f32_e32 v74, v74
	v_exp_f32_e32 v75, v75
	v_exp_f32_e32 v76, v76
	v_exp_f32_e32 v77, v77
	v_exp_f32_e32 v78, v78
	v_exp_f32_e32 v79, v79
	v_exp_f32_e32 v80, v80
	s_waitcnt lgkmcnt(5)
	v_mfma_f32_32x32x16_bf16 v[82:97], v[232:235], v[154:157], v[82:97]
	ds_read_b128 v[208:211], v252 offset:39424
	v_exp_f32_e32 v81, v81
	v_pk_add_f32 v[184:185], v[66:67], v[68:69]
	v_pk_add_f32 v[186:187], v[70:71], v[72:73]
	v_pk_add_f32 v[184:185], v[184:185], v[74:75]
	v_pk_add_f32 v[186:187], v[186:187], v[76:77]
	v_pk_add_f32 v[184:185], v[184:185], v[78:79]
	v_pk_add_f32 v[186:187], v[186:187], v[80:81]
	s_waitcnt lgkmcnt(5)
	v_mfma_f32_32x32x16_bf16 v[82:97], v[236:239], v[158:161], v[82:97]
	ds_read_b128 v[212:215], v252 offset:25632
	v_cvt_pk_bf16_f32 v66, v66, v67
	v_cvt_pk_bf16_f32 v67, v68, v69
	v_cvt_pk_bf16_f32 v68, v70, v71
	v_cvt_pk_bf16_f32 v69, v72, v73
	v_cvt_pk_bf16_f32 v70, v74, v75
	v_cvt_pk_bf16_f32 v71, v76, v77
	v_cvt_pk_bf16_f32 v72, v78, v79
	s_waitcnt lgkmcnt(5)
	v_mfma_f32_32x32x16_bf16 v[82:97], v[240:243], v[162:165], v[82:97]
	ds_read_b128 v[216:219], v252 offset:30240
	v_cvt_pk_bf16_f32 v73, v80, v81
	v_pk_add_f32 v[184:185], v[184:185], v[186:187]
	v_add_f32_e32 v184, v184, v185
	v_add_f32_e32 v182, v182, v184
	s_nop 1
	s_waitcnt lgkmcnt(5)
	v_mfma_f32_32x32x16_bf16 v[50:65], v[196:199], v[66:69], v[50:65]
	ds_read_b128 v[220:223], v252 offset:34848
	s_bitcmp1_b32 s51, 0
	s_cselect_b32 s99, 0xac00, 0
	s_add_i32 s99, s99, 0
	v_add_u32_e32 v250, s99, v170
	s_waitcnt lgkmcnt(5)
	v_mfma_f32_32x32x16_bf16 v[34:49], v[200:203], v[66:69], v[34:49]
	ds_read_b128 v[224:227], v252 offset:39456
	s_waitcnt vmcnt(4)
	ds_write_b128 v250, v[98:101]
	s_waitcnt vmcnt(3)
	ds_write_b128 v250, v[102:105] offset:12800
	s_waitcnt lgkmcnt(7)
	v_mfma_f32_32x32x16_bf16 v[18:33], v[204:207], v[66:69], v[18:33]
	ds_read_b128 v[228:231], v252 offset:25664
	v_max3_f32 v0, v82, v83, v84
	v_max3_f32 v184, v85, v86, v87
	v_max3_f32 v0, v0, v88, v89
	v_max3_f32 v184, v184, v90, v91
	v_max3_f32 v0, v0, v92, v93
	v_max3_f32 v184, v184, v94, v95
	v_max3_f32 v0, v0, v96, v97
	s_waitcnt lgkmcnt(7)
	v_mfma_f32_32x32x16_bf16 v[2:17], v[208:211], v[66:69], v[2:17]
	ds_read_b128 v[232:235], v252 offset:30272
	v_max_f32_e32 v0, v0, v184
	v_mov_b32_e32 v184, v0
	s_nop 1
	v_permlane32_swap_b32_e32 v0, v184
	v_max_f32_e32 v184, v184, v184
	v_max_f32_e32 v0, v0, v0
	v_max_f32_e32 v0, v0, v184
	s_waitcnt lgkmcnt(7)
	v_mfma_f32_32x32x16_bf16 v[50:65], v[212:215], v[70:73], v[50:65]
	ds_read_b128 v[236:239], v252 offset:34880
	v_sub_f32_e32 v184, v0, v183
	v_cmp_lt_f32_e32 vcc, s43, v184
	s_cbranch_vccnz .LaG1_R1
.LaG1_R1b:
	v_sub_f32_e32 v82, v82, v183
	v_sub_f32_e32 v83, v83, v183
	v_sub_f32_e32 v84, v84, v183
	s_waitcnt lgkmcnt(7)
	v_mfma_f32_32x32x16_bf16 v[34:49], v[216:219], v[70:73], v[34:49]
	ds_read_b128 v[240:243], v252 offset:39488
	v_sub_f32_e32 v85, v85, v183
	v_sub_f32_e32 v86, v86, v183
	v_sub_f32_e32 v87, v87, v183
	v_sub_f32_e32 v88, v88, v183
	v_sub_f32_e32 v89, v89, v183
	v_exp_f32_e32 v82, v82
	v_exp_f32_e32 v83, v83
	s_waitcnt lgkmcnt(7)
	v_mfma_f32_32x32x16_bf16 v[18:33], v[220:223], v[70:73], v[18:33]
	ds_read_b128 v[196:199], v252 offset:25696
	v_exp_f32_e32 v84, v84
	v_exp_f32_e32 v85, v85
	v_exp_f32_e32 v86, v86
	v_exp_f32_e32 v87, v87
	v_exp_f32_e32 v88, v88
	v_exp_f32_e32 v89, v89
	v_cvt_pk_bf16_f32 v74, v82, v83
	s_waitcnt lgkmcnt(7)
	v_mfma_f32_32x32x16_bf16 v[2:17], v[224:227], v[70:73], v[2:17]
	ds_read_b128 v[200:203], v252 offset:30304
	v_cvt_pk_bf16_f32 v75, v84, v85
	v_cvt_pk_bf16_f32 v76, v86, v87
	v_cvt_pk_bf16_f32 v77, v88, v89
	v_pk_add_f32 v[184:185], v[82:83], v[84:85]
	v_pk_add_f32 v[186:187], v[86:87], v[88:89]
	s_cmp_lg_u32 s98, 0
	s_cbranch_scc1 .LaG1_R1x
.LaG1_R1xb:
	s_nop 1
	s_waitcnt lgkmcnt(5)
	v_mfma_f32_32x32x16_bf16 v[50:65], v[228:231], v[74:77], v[50:65]
	ds_read_b128 v[204:207], v252 offset:34912
	v_sub_f32_e32 v90, v90, v183
	v_sub_f32_e32 v91, v91, v183
	v_sub_f32_e32 v92, v92, v183
	v_sub_f32_e32 v93, v93, v183
	v_sub_f32_e32 v94, v94, v183
	v_sub_f32_e32 v95, v95, v183
	s_waitcnt lgkmcnt(5)
	v_mfma_f32_32x32x16_bf16 v[34:49], v[232:235], v[74:77], v[34:49]
	ds_read_b128 v[208:211], v252 offset:39520
	v_sub_f32_e32 v96, v96, v183
	v_sub_f32_e32 v97, v97, v183
	v_exp_f32_e32 v90, v90
	v_exp_f32_e32 v91, v91
	v_exp_f32_e32 v92, v92
	v_exp_f32_e32 v93, v93
	s_waitcnt lgkmcnt(5)
	v_mfma_f32_32x32x16_bf16 v[18:33], v[236:239], v[74:77], v[18:33]
	v_exp_f32_e32 v94, v94
	v_exp_f32_e32 v95, v95
	v_exp_f32_e32 v96, v96
	v_exp_f32_e32 v97, v97
	v_cvt_pk_bf16_f32 v78, v90, v91
	v_cvt_pk_bf16_f32 v79, v92, v93
	s_waitcnt lgkmcnt(4)
	v_mfma_f32_32x32x16_bf16 v[2:17], v[240:243], v[74:77], v[2:17]
	v_cvt_pk_bf16_f32 v80, v94, v95
	v_cvt_pk_bf16_f32 v81, v96, v97
	v_pk_add_f32 v[184:185], v[184:185], v[90:91]
	v_pk_add_f32 v[186:187], v[186:187], v[92:93]
	v_pk_add_f32 v[184:185], v[184:185], v[94:95]
	v_pk_add_f32 v[186:187], v[186:187], v[96:97]
	s_nop 1
	s_waitcnt lgkmcnt(3)
	v_mfma_f32_32x32x16_bf16 v[50:65], v[196:199], v[78:81], v[50:65]
	v_add_u32_e32 v250, s99, v172
	s_waitcnt vmcnt(2)
	ds_write_b128 v250, v[106:109] offset:256
	s_waitcnt lgkmcnt(3)
	v_mfma_f32_32x32x16_bf16 v[34:49], v[200:203], v[78:81], v[34:49]
	v_add_u32_e32 v250, s99, v169
	s_waitcnt vmcnt(1)
	ds_write_b128 v250, v[114:117] offset:25600
	s_waitcnt lgkmcnt(3)
	v_mfma_f32_32x32x16_bf16 v[18:33], v[204:207], v[78:81], v[18:33]
	s_waitcnt vmcnt(0)
	ds_write_b128 v250, v[146:149] offset:34816
	v_pk_add_f32 v[184:185], v[184:185], v[186:187]
	s_waitcnt lgkmcnt(3)
	v_mfma_f32_32x32x16_bf16 v[2:17], v[208:211], v[78:81], v[2:17]
	v_add_f32_e32 v184, v184, v185
	v_add_f32_e32 v182, v182, v184
	s_setprio 0
	s_branch .LBB0_1478
.LaG1_R0:
	v_max_f32_e32 v0, v0, v0
	v_max_f32_e32 v184, v183, v183
	v_max_f32_e32 v184, v184, v0
	v_sub_f32_e32 v0, v183, v184
	v_exp_f32_e32 v0, v0
	v_mov_b32_e32 v183, v184
	v_pk_mul_f32 v[64:65], v[64:65], v[0:1] op_sel_hi:[1,0]
	v_pk_mul_f32 v[62:63], v[62:63], v[0:1] op_sel_hi:[1,0]
	v_pk_mul_f32 v[60:61], v[60:61], v[0:1] op_sel_hi:[1,0]
	v_pk_mul_f32 v[58:59], v[58:59], v[0:1] op_sel_hi:[1,0]
	v_pk_mul_f32 v[56:57], v[56:57], v[0:1] op_sel_hi:[1,0]
	v_pk_mul_f32 v[54:55], v[54:55], v[0:1] op_sel_hi:[1,0]
	v_pk_mul_f32 v[52:53], v[52:53], v[0:1] op_sel_hi:[1,0]
	v_pk_mul_f32 v[50:51], v[50:51], v[0:1] op_sel_hi:[1,0]
	v_pk_mul_f32 v[48:49], v[48:49], v[0:1] op_sel_hi:[1,0]
	v_pk_mul_f32 v[46:47], v[46:47], v[0:1] op_sel_hi:[1,0]
	v_pk_mul_f32 v[44:45], v[44:45], v[0:1] op_sel_hi:[1,0]
	v_pk_mul_f32 v[42:43], v[42:43], v[0:1] op_sel_hi:[1,0]
	v_pk_mul_f32 v[40:41], v[40:41], v[0:1] op_sel_hi:[1,0]
	v_pk_mul_f32 v[38:39], v[38:39], v[0:1] op_sel_hi:[1,0]
	v_pk_mul_f32 v[36:37], v[36:37], v[0:1] op_sel_hi:[1,0]
	v_pk_mul_f32 v[34:35], v[34:35], v[0:1] op_sel_hi:[1,0]
	v_pk_mul_f32 v[32:33], v[32:33], v[0:1] op_sel_hi:[1,0]
	v_pk_mul_f32 v[30:31], v[30:31], v[0:1] op_sel_hi:[1,0]
	v_pk_mul_f32 v[28:29], v[28:29], v[0:1] op_sel_hi:[1,0]
	v_pk_mul_f32 v[26:27], v[26:27], v[0:1] op_sel_hi:[1,0]
	v_pk_mul_f32 v[24:25], v[24:25], v[0:1] op_sel_hi:[1,0]
	v_pk_mul_f32 v[22:23], v[22:23], v[0:1] op_sel_hi:[1,0]
	v_pk_mul_f32 v[20:21], v[20:21], v[0:1] op_sel_hi:[1,0]
	v_pk_mul_f32 v[18:19], v[18:19], v[0:1] op_sel_hi:[1,0]
	v_pk_mul_f32 v[16:17], v[16:17], v[0:1] op_sel_hi:[1,0]
	v_pk_mul_f32 v[14:15], v[14:15], v[0:1] op_sel_hi:[1,0]
	v_pk_mul_f32 v[12:13], v[12:13], v[0:1] op_sel_hi:[1,0]
	v_pk_mul_f32 v[10:11], v[10:11], v[0:1] op_sel_hi:[1,0]
	v_pk_mul_f32 v[8:9], v[8:9], v[0:1] op_sel_hi:[1,0]
	v_pk_mul_f32 v[6:7], v[6:7], v[0:1] op_sel_hi:[1,0]
	v_pk_mul_f32 v[4:5], v[4:5], v[0:1] op_sel_hi:[1,0]
	v_pk_mul_f32 v[2:3], v[2:3], v[0:1] op_sel_hi:[1,0]
	v_mul_f32_e32 v182, v182, v0
	s_branch .LaG1_R0b
.LaG1_R1:
	v_max_f32_e32 v0, v0, v0
	v_max_f32_e32 v184, v183, v183
	v_max_f32_e32 v184, v184, v0
	v_sub_f32_e32 v0, v183, v184
	v_exp_f32_e32 v0, v0
	v_mov_b32_e32 v183, v184
	v_mov_b32_e32 v249, v0
	s_mov_b32 s98, 1
	s_branch .LaG1_R1b
.LaG1_R1x:
	s_nop 15
	s_nop 15
	s_nop 15
	s_nop 15
	s_nop 15
	s_nop 15
	v_mov_b32_e32 v0, v249
	v_pk_mul_f32 v[64:65], v[64:65], v[0:1] op_sel_hi:[1,0]
	v_pk_mul_f32 v[62:63], v[62:63], v[0:1] op_sel_hi:[1,0]
	v_pk_mul_f32 v[60:61], v[60:61], v[0:1] op_sel_hi:[1,0]
	v_pk_mul_f32 v[58:59], v[58:59], v[0:1] op_sel_hi:[1,0]
	v_pk_mul_f32 v[56:57], v[56:57], v[0:1] op_sel_hi:[1,0]
	v_pk_mul_f32 v[54:55], v[54:55], v[0:1] op_sel_hi:[1,0]
	v_pk_mul_f32 v[52:53], v[52:53], v[0:1] op_sel_hi:[1,0]
	v_pk_mul_f32 v[50:51], v[50:51], v[0:1] op_sel_hi:[1,0]
	v_pk_mul_f32 v[48:49], v[48:49], v[0:1] op_sel_hi:[1,0]
	v_pk_mul_f32 v[46:47], v[46:47], v[0:1] op_sel_hi:[1,0]
	v_pk_mul_f32 v[44:45], v[44:45], v[0:1] op_sel_hi:[1,0]
	v_pk_mul_f32 v[42:43], v[42:43], v[0:1] op_sel_hi:[1,0]
	v_pk_mul_f32 v[40:41], v[40:41], v[0:1] op_sel_hi:[1,0]
	v_pk_mul_f32 v[38:39], v[38:39], v[0:1] op_sel_hi:[1,0]
	v_pk_mul_f32 v[36:37], v[36:37], v[0:1] op_sel_hi:[1,0]
	v_pk_mul_f32 v[34:35], v[34:35], v[0:1] op_sel_hi:[1,0]
	v_pk_mul_f32 v[32:33], v[32:33], v[0:1] op_sel_hi:[1,0]
	v_pk_mul_f32 v[30:31], v[30:31], v[0:1] op_sel_hi:[1,0]
	v_pk_mul_f32 v[28:29], v[28:29], v[0:1] op_sel_hi:[1,0]
	v_pk_mul_f32 v[26:27], v[26:27], v[0:1] op_sel_hi:[1,0]
	v_pk_mul_f32 v[24:25], v[24:25], v[0:1] op_sel_hi:[1,0]
	v_pk_mul_f32 v[22:23], v[22:23], v[0:1] op_sel_hi:[1,0]
	v_pk_mul_f32 v[20:21], v[20:21], v[0:1] op_sel_hi:[1,0]
	v_pk_mul_f32 v[18:19], v[18:19], v[0:1] op_sel_hi:[1,0]
	v_pk_mul_f32 v[16:17], v[16:17], v[0:1] op_sel_hi:[1,0]
	v_pk_mul_f32 v[14:15], v[14:15], v[0:1] op_sel_hi:[1,0]
	v_pk_mul_f32 v[12:13], v[12:13], v[0:1] op_sel_hi:[1,0]
	v_pk_mul_f32 v[10:11], v[10:11], v[0:1] op_sel_hi:[1,0]
	v_pk_mul_f32 v[8:9], v[8:9], v[0:1] op_sel_hi:[1,0]
	v_pk_mul_f32 v[6:7], v[6:7], v[0:1] op_sel_hi:[1,0]
	v_pk_mul_f32 v[4:5], v[4:5], v[0:1] op_sel_hi:[1,0]
	v_pk_mul_f32 v[2:3], v[2:3], v[0:1] op_sel_hi:[1,0]
	v_mul_f32_e32 v182, v182, v0
	s_mov_b32 s98, 0
	s_nop 1
	s_branch .LaG1_R1xb

.LaF2_fast:
	s_add_i32 s26, s37, 63
	s_cmp_le_i32 s26, s30
	s_cbranch_scc1 .LaG2_fast
	s_waitcnt vmcnt(0)
	s_bitcmp1_b32 s36, 0
	s_cselect_b32 s4, 0, 0xac00
	s_setprio 1
	v_add_u32_e32 v253, s4, v171
	v_add_u32_e32 v252, s4, v181
	ds_read_b128 v[196:199], v253
	ds_read_b128 v[200:203], v253 offset:12800
	ds_read_b128 v[204:207], v253 offset:32
	ds_read_b128 v[208:211], v253 offset:12832
	ds_read_b128 v[212:215], v253 offset:64
	ds_read_b128 v[216:219], v253 offset:12864
	s_waitcnt lgkmcnt(5)
	v_mfma_f32_32x32x16_bf16 v[66:81], v[196:199], v[110:113], 0
	ds_read_b128 v[220:223], v253 offset:96
	v_lshl_add_u64 v[244:245], s[2:3], 0, v[176:177]
	s_waitcnt lgkmcnt(5)
	v_mfma_f32_32x32x16_bf16 v[82:97], v[200:203], v[110:113], 0
	ds_read_b128 v[224:227], v253 offset:12896
	v_add_co_u32_e32 v246, vcc, 0x16020000, v244
	s_waitcnt lgkmcnt(5)
	v_mfma_f32_32x32x16_bf16 v[66:81], v[204:207], v[114:117], v[66:81]
	ds_read_b128 v[228:231], v253 offset:128
	s_nop 1
	s_waitcnt lgkmcnt(5)
	v_mfma_f32_32x32x16_bf16 v[82:97], v[208:211], v[114:117], v[82:97]
	ds_read_b128 v[232:235], v253 offset:12928
	v_addc_co_u32_e32 v247, vcc, 0, v245, vcc
	s_waitcnt lgkmcnt(5)
	v_mfma_f32_32x32x16_bf16 v[66:81], v[212:215], v[118:121], v[66:81]
	ds_read_b128 v[236:239], v253 offset:160
	v_add_co_u32_e32 v244, vcc, 0x16030000, v244
	s_waitcnt lgkmcnt(5)
	v_mfma_f32_32x32x16_bf16 v[82:97], v[216:219], v[118:121], v[82:97]
	ds_read_b128 v[240:243], v253 offset:12960
	s_nop 1
	s_waitcnt lgkmcnt(5)
	v_mfma_f32_32x32x16_bf16 v[66:81], v[220:223], v[122:125], v[66:81]
	ds_read_b128 v[196:199], v253 offset:192
	v_addc_co_u32_e32 v245, vcc, 0, v245, vcc
	s_waitcnt lgkmcnt(5)
	v_mfma_f32_32x32x16_bf16 v[82:97], v[224:227], v[122:125], v[82:97]
	ds_read_b128 v[200:203], v253 offset:12992
	global_load_dwordx4 v[98:101], v[246:247], off
	s_waitcnt lgkmcnt(5)
	v_mfma_f32_32x32x16_bf16 v[66:81], v[228:231], v[130:133], v[66:81]
	ds_read_b128 v[204:207], v253 offset:224
	global_load_dwordx4 v[102:105], v[244:245], off
	s_waitcnt lgkmcnt(5)
	v_mfma_f32_32x32x16_bf16 v[82:97], v[232:235], v[130:133], v[82:97]
	ds_read_b128 v[208:211], v253 offset:13024
	v_lshl_add_u64 v[246:247], s[2:3], 0, v[178:179]
	s_waitcnt lgkmcnt(5)
	v_mfma_f32_32x32x16_bf16 v[66:81], v[236:239], v[134:137], v[66:81]
	ds_read_b128 v[212:215], v253 offset:256
	v_add_co_u32_e32 v248, vcc, 0x1a000000, v246
	s_waitcnt lgkmcnt(5)
	v_mfma_f32_32x32x16_bf16 v[82:97], v[240:243], v[134:137], v[82:97]
	ds_read_b128 v[216:219], v253 offset:13056
	v_lshl_add_u64 v[244:245], s[2:3], 0, v[174:175]
	s_waitcnt lgkmcnt(5)
	v_mfma_f32_32x32x16_bf16 v[66:81], v[196:199], v[138:141], v[66:81]
	ds_read_b128 v[220:223], v253 offset:288
	s_nop 0
	s_waitcnt lgkmcnt(5)
	v_mfma_f32_32x32x16_bf16 v[82:97], v[200:203], v[138:141], v[82:97]
	ds_read_b128 v[224:227], v253 offset:13088
	v_addc_co_u32_e32 v249, vcc, 0, v247, vcc
	s_waitcnt lgkmcnt(5)
	v_mfma_f32_32x32x16_bf16 v[66:81], v[204:207], v[142:145], v[66:81]
	ds_read_b128 v[228:231], v253 offset:320
	global_load_dwordx4 v[106:109], v[244:245], off
	s_waitcnt lgkmcnt(5)
	v_mfma_f32_32x32x16_bf16 v[82:97], v[208:211], v[142:145], v[82:97]
	ds_read_b128 v[232:235], v253 offset:13120
	global_load_dwordx4 v[126:129], v[248:249], off offset:128
	s_waitcnt lgkmcnt(5)
	v_mfma_f32_32x32x16_bf16 v[66:81], v[212:215], v[146:149], v[66:81]
	ds_read_b128 v[236:239], v253 offset:352
	v_add_co_u32_e32 v244, vcc, 0x1a400000, v246
	s_waitcnt lgkmcnt(5)
	v_mfma_f32_32x32x16_bf16 v[82:97], v[216:219], v[146:149], v[82:97]
	ds_read_b128 v[240:243], v253 offset:13152
	s_nop 1
	s_waitcnt lgkmcnt(5)
	v_mfma_f32_32x32x16_bf16 v[66:81], v[220:223], v[154:157], v[66:81]
	v_addc_co_u32_e32 v245, vcc, 0, v247, vcc
	s_waitcnt lgkmcnt(4)
	v_mfma_f32_32x32x16_bf16 v[82:97], v[224:227], v[154:157], v[82:97]
	global_load_dwordx4 v[150:153], v[244:245], off offset:128
	s_waitcnt lgkmcnt(3)
	v_mfma_f32_32x32x16_bf16 v[66:81], v[228:231], v[158:161], v[66:81]
	s_waitcnt lgkmcnt(2)
	v_mfma_f32_32x32x16_bf16 v[82:97], v[232:235], v[158:161], v[82:97]
	s_waitcnt lgkmcnt(1)
	v_mfma_f32_32x32x16_bf16 v[66:81], v[236:239], v[162:165], v[66:81]
	s_waitcnt lgkmcnt(0)
	v_mfma_f32_32x32x16_bf16 v[82:97], v[240:243], v[162:165], v[82:97]
	ds_read_b128 v[196:199], v252 offset:25600
	ds_read_b128 v[200:203], v252 offset:30208
	ds_read_b128 v[204:207], v252 offset:34816
	ds_read_b128 v[208:211], v252 offset:39424
	ds_read_b128 v[212:215], v252 offset:25632
	ds_read_b128 v[216:219], v252 offset:30240
	s_setprio 0
	s_add_i32 s26, s37, 63
	s_cmp_le_i32 s26, s30
	s_cbranch_scc1 .LaF2_1
	v_add_u32_e32 v0, s37, v168
	v_add_u32_e32 v184, 32, v0
	v_cmp_le_i32_e32 vcc, v184, v173
	v_add_u32_e32 v184, 33, v0
	s_nop 3
	v_cndmask_b32_e32 v82, v180, v82, vcc
	v_cmp_lt_i32_e32 vcc, v0, v173
	s_nop 1
	v_cndmask_b32_e32 v67, v180, v67, vcc
	v_cmp_le_i32_e32 vcc, v0, v173
	s_nop 1
	v_cndmask_b32_e32 v66, v180, v66, vcc
	v_cmp_le_i32_e32 vcc, v184, v173
	v_add_u32_e32 v184, 2, v0
	s_nop 0
	v_cndmask_b32_e32 v83, v180, v83, vcc
	v_cmp_le_i32_e32 vcc, v184, v173
	v_add_u32_e32 v184, 34, v0
	s_nop 0
	v_cndmask_b32_e32 v68, v180, v68, vcc
	v_cmp_le_i32_e32 vcc, v184, v173
	v_add_u32_e32 v184, 3, v0
	s_nop 0
	v_cndmask_b32_e32 v84, v180, v84, vcc
	v_cmp_le_i32_e32 vcc, v184, v173
	v_add_u32_e32 v184, 35, v0
	s_nop 0
	v_cndmask_b32_e32 v69, v180, v69, vcc
	v_cmp_le_i32_e32 vcc, v184, v173
	v_add_u32_e32 v184, 4, v0
	s_nop 0
	v_cndmask_b32_e32 v85, v180, v85, vcc
	v_cmp_le_i32_e32 vcc, v184, v173
	v_add_u32_e32 v184, 36, v0
	s_nop 0
	v_cndmask_b32_e32 v70, v180, v70, vcc
	v_cmp_le_i32_e32 vcc, v184, v173
	v_add_u32_e32 v184, 5, v0
	s_nop 0
	v_cndmask_b32_e32 v86, v180, v86, vcc
	v_cmp_le_i32_e32 vcc, v184, v173
	v_add_u32_e32 v184, 37, v0
	s_nop 0
	v_cndmask_b32_e32 v71, v180, v71, vcc
	v_cmp_le_i32_e32 vcc, v184, v173
	v_add_u32_e32 v184, 6, v0
	s_nop 0
	v_cndmask_b32_e32 v87, v180, v87, vcc
	v_cmp_le_i32_e32 vcc, v184, v173
	v_add_u32_e32 v184, 38, v0
	s_nop 0
	v_cndmask_b32_e32 v72, v180, v72, vcc
	v_cmp_le_i32_e32 vcc, v184, v173
	v_add_u32_e32 v184, 7, v0
	s_nop 0
	v_cndmask_b32_e32 v88, v180, v88, vcc
	v_cmp_le_i32_e32 vcc, v184, v173
	v_add_u32_e32 v184, 39, v0
	s_nop 0
	v_cndmask_b32_e32 v73, v180, v73, vcc
	v_cmp_le_i32_e32 vcc, v184, v173
	v_add_u32_e32 v184, 16, v0
	s_nop 0
	v_cndmask_b32_e32 v89, v180, v89, vcc
	v_cmp_le_i32_e32 vcc, v184, v173
	v_add_u32_e32 v184, 48, v0
	s_nop 0
	v_cndmask_b32_e32 v74, v180, v74, vcc
	v_cmp_le_i32_e32 vcc, v184, v173
	v_add_u32_e32 v184, 17, v0
	s_nop 0
	v_cndmask_b32_e32 v90, v180, v90, vcc
	v_cmp_le_i32_e32 vcc, v184, v173
	v_add_u32_e32 v184, 49, v0
	s_nop 0
	v_cndmask_b32_e32 v75, v180, v75, vcc
	v_cmp_le_i32_e32 vcc, v184, v173
	v_add_u32_e32 v184, 18, v0
	s_nop 0
	v_cndmask_b32_e32 v91, v180, v91, vcc
	v_cmp_le_i32_e32 vcc, v184, v173
	v_add_u32_e32 v184, 50, v0
	s_nop 0
	v_cndmask_b32_e32 v76, v180, v76, vcc
	v_cmp_le_i32_e32 vcc, v184, v173
	v_add_u32_e32 v184, 19, v0
	s_nop 0
	v_cndmask_b32_e32 v92, v180, v92, vcc
	v_cmp_le_i32_e32 vcc, v184, v173
	v_add_u32_e32 v184, 51, v0
	s_nop 0
	v_cndmask_b32_e32 v77, v180, v77, vcc
	v_cmp_le_i32_e32 vcc, v184, v173
	v_add_u32_e32 v184, 20, v0
	s_nop 0
	v_cndmask_b32_e32 v93, v180, v93, vcc
	v_cmp_le_i32_e32 vcc, v184, v173
	v_add_u32_e32 v184, 52, v0
	s_nop 0
	v_cndmask_b32_e32 v78, v180, v78, vcc
	v_cmp_le_i32_e32 vcc, v184, v173
	v_add_u32_e32 v184, 21, v0
	s_nop 0
	v_cndmask_b32_e32 v94, v180, v94, vcc
	v_cmp_le_i32_e32 vcc, v184, v173
	v_add_u32_e32 v184, 53, v0
	s_nop 0
	v_cndmask_b32_e32 v79, v180, v79, vcc
	v_cmp_le_i32_e32 vcc, v184, v173
	v_add_u32_e32 v184, 22, v0
	s_nop 0
	v_cndmask_b32_e32 v95, v180, v95, vcc
	v_cmp_le_i32_e32 vcc, v184, v173
	v_add_u32_e32 v184, 54, v0
	s_nop 0
	v_cndmask_b32_e32 v80, v180, v80, vcc
	v_cmp_le_i32_e32 vcc, v184, v173
	v_add_u32_e32 v184, 23, v0
	v_add_u32_e32 v0, 55, v0
	v_cndmask_b32_e32 v96, v180, v96, vcc
	v_cmp_le_i32_e32 vcc, v184, v173
	s_nop 1
	v_cndmask_b32_e32 v81, v180, v81, vcc
	v_cmp_le_i32_e32 vcc, v0, v173
	s_nop 1
	v_cndmask_b32_e32 v97, v180, v97, vcc

.LaG2_fast:
	s_waitcnt vmcnt(0)
	s_bitcmp1_b32 s36, 0
	s_cselect_b32 s4, 0, 0xac00
	s_mov_b32 s98, 0
	s_setprio 1
	v_add_u32_e32 v253, s4, v171
	v_add_u32_e32 v252, s4, v181
	ds_read_b128 v[196:199], v253
	ds_read_b128 v[200:203], v253 offset:32
	ds_read_b128 v[204:207], v253 offset:64
	ds_read_b128 v[208:211], v253 offset:96
	ds_read_b128 v[212:215], v253 offset:128
	ds_read_b128 v[216:219], v253 offset:160
	s_waitcnt lgkmcnt(5)
	v_mfma_f32_32x32x16_bf16 v[66:81], v[196:199], v[110:113], 0
	ds_read_b128 v[220:223], v253 offset:192
	v_lshl_add_u64 v[244:245], s[2:3], 0, v[176:177]
	v_add_co_u32_e32 v246, vcc, 0x16020000, v244
	s_waitcnt lgkmcnt(5)
	v_mfma_f32_32x32x16_bf16 v[66:81], v[200:203], v[114:117], v[66:81]
	ds_read_b128 v[224:227], v253 offset:224
	s_nop 1
	v_addc_co_u32_e32 v247, vcc, 0, v245, vcc
	s_waitcnt lgkmcnt(5)
	v_mfma_f32_32x32x16_bf16 v[66:81], v[204:207], v[118:121], v[66:81]
	ds_read_b128 v[228:231], v253 offset:256
	v_add_co_u32_e32 v244, vcc, 0x16030000, v244
	s_nop 1
	s_waitcnt lgkmcnt(5)
	v_mfma_f32_32x32x16_bf16 v[66:81], v[208:211], v[122:125], v[66:81]
	ds_read_b128 v[232:235], v253 offset:288
	v_addc_co_u32_e32 v245, vcc, 0, v245, vcc
	global_load_dwordx4 v[98:101], v[246:247], off
	s_waitcnt lgkmcnt(5)
	v_mfma_f32_32x32x16_bf16 v[66:81], v[212:215], v[130:133], v[66:81]
	ds_read_b128 v[236:239], v253 offset:320
	global_load_dwordx4 v[102:105], v[244:245], off
	v_lshl_add_u64 v[246:247], s[2:3], 0, v[178:179]
	s_waitcnt lgkmcnt(5)
	v_mfma_f32_32x32x16_bf16 v[66:81], v[216:219], v[134:137], v[66:81]
	ds_read_b128 v[240:243], v253 offset:352
	v_add_co_u32_e32 v248, vcc, 0x1a000000, v246
	v_lshl_add_u64 v[244:245], s[2:3], 0, v[174:175]
	s_waitcnt lgkmcnt(5)
	v_mfma_f32_32x32x16_bf16 v[66:81], v[220:223], v[138:141], v[66:81]
	ds_read_b128 v[196:199], v253 offset:12800
	s_nop 0
	v_addc_co_u32_e32 v249, vcc, 0, v247, vcc
	s_waitcnt lgkmcnt(5)
	v_mfma_f32_32x32x16_bf16 v[66:81], v[224:227], v[142:145], v[66:81]
	ds_read_b128 v[200:203], v253 offset:12832
	global_load_dwordx4 v[106:109], v[244:245], off
	global_load_dwordx4 v[126:129], v[248:249], off offset:128
	s_waitcnt lgkmcnt(5)
	v_mfma_f32_32x32x16_bf16 v[66:81], v[228:231], v[146:149], v[66:81]
	ds_read_b128 v[204:207], v253 offset:12864
	v_add_co_u32_e32 v244, vcc, 0x1a400000, v246
	s_nop 1
	s_waitcnt lgkmcnt(5)
	v_mfma_f32_32x32x16_bf16 v[66:81], v[232:235], v[154:157], v[66:81]
	ds_read_b128 v[208:211], v253 offset:12896
	v_addc_co_u32_e32 v245, vcc, 0, v247, vcc
	global_load_dwordx4 v[150:153], v[244:245], off offset:128
	s_waitcnt lgkmcnt(5)
	v_mfma_f32_32x32x16_bf16 v[66:81], v[236:239], v[158:161], v[66:81]
	ds_read_b128 v[212:215], v253 offset:12928
	s_waitcnt lgkmcnt(5)
	v_mfma_f32_32x32x16_bf16 v[66:81], v[240:243], v[162:165], v[66:81]
	ds_read_b128 v[216:219], v253 offset:12960
	s_waitcnt lgkmcnt(5)
	v_mfma_f32_32x32x16_bf16 v[82:97], v[196:199], v[110:113], 0
	ds_read_b128 v[220:223], v253 offset:12992
	s_waitcnt lgkmcnt(5)
	v_mfma_f32_32x32x16_bf16 v[82:97], v[200:203], v[114:117], v[82:97]
	ds_read_b128 v[224:227], v253 offset:13024
	s_waitcnt lgkmcnt(5)
	v_mfma_f32_32x32x16_bf16 v[82:97], v[204:207], v[118:121], v[82:97]
	ds_read_b128 v[228:231], v253 offset:13056
	v_max3_f32 v0, v66, v67, v68
	v_max3_f32 v184, v69, v70, v71
	v_max3_f32 v0, v0, v72, v73
	v_max3_f32 v184, v184, v74, v75
	v_max3_f32 v0, v0, v76, v77
	v_max3_f32 v184, v184, v78, v79
	v_max3_f32 v0, v0, v80, v81
	s_waitcnt lgkmcnt(5)
	v_mfma_f32_32x32x16_bf16 v[82:97], v[208:211], v[122:125], v[82:97]
	ds_read_b128 v[232:235], v253 offset:13088
	v_max_f32_e32 v0, v0, v184
	v_mov_b32_e32 v184, v0
	s_nop 1
	v_permlane32_swap_b32_e32 v0, v184
	v_max_f32_e32 v184, v184, v184
	v_max_f32_e32 v0, v0, v0
	v_max_f32_e32 v0, v0, v184
	s_waitcnt lgkmcnt(5)
	v_mfma_f32_32x32x16_bf16 v[82:97], v[212:215], v[130:133], v[82:97]
	ds_read_b128 v[236:239], v253 offset:13120
	v_sub_f32_e32 v184, v0, v183
	v_cmp_lt_f32_e32 vcc, s43, v184
	s_cbranch_vccnz .LaG2_R0
.LaG2_R0b:
	v_sub_f32_e32 v66, v66, v183
	v_sub_f32_e32 v67, v67, v183
	v_sub_f32_e32 v68, v68, v183
	s_waitcnt lgkmcnt(5)
	v_mfma_f32_32x32x16_bf16 v[82:97], v[216:219], v[134:137], v[82:97]
	ds_read_b128 v[240:243], v253 offset:13152
	v_sub_f32_e32 v69, v69, v183
	v_sub_f32_e32 v70, v70, v183
	v_sub_f32_e32 v71, v71, v183
	v_sub_f32_e32 v72, v72, v183
	v_sub_f32_e32 v73, v73, v183
	v_sub_f32_e32 v74, v74, v183
	v_sub_f32_e32 v75, v75, v183
	s_waitcnt lgkmcnt(5)
	v_mfma_f32_32x32x16_bf16 v[82:97], v[220:223], v[138:141], v[82:97]
	ds_read_b128 v[196:199], v252 offset:25600
	v_sub_f32_e32 v76, v76, v183
	v_sub_f32_e32 v77, v77, v183
	v_sub_f32_e32 v78, v78, v183
	v_sub_f32_e32 v79, v79, v183
	v_sub_f32_e32 v80, v80, v183
	v_sub_f32_e32 v81, v81, v183
	v_exp_f32_e32 v66, v66
	s_waitcnt lgkmcnt(5)
	v_mfma_f32_32x32x16_bf16 v[82:97], v[224:227], v[142:145], v[82:97]
	ds_read_b128 v[200:203], v252 offset:30208
	v_exp_f32_e32 v67, v67
	v_exp_f32_e32 v68, v68
	v_exp_f32_e32 v69, v69
	v_exp_f32_e32 v70, v70
	v_exp_f32_e32 v71, v71
	v_exp_f32_e32 v72, v72
	v_exp_f32_e32 v73, v73
	s_waitcnt lgkmcnt(5)
	v_mfma_f32_32x32x16_bf16 v[82:97], v[228:231], v[146:149], v[82:97]
	ds_read_b128 v[204:207], v252 offset:34816
	v_exp_f32_e32 v74, v74
	v_exp_f32_e32 v75, v75
	v_exp_f32_e32 v76, v76
	v_exp_f32_e32 v77, v77
	v_exp_f32_e32 v78, v78
	v_exp_f32_e32 v79, v79
	v_exp_f32_e32 v80, v80
	s_waitcnt lgkmcnt(5)
	v_mfma_f32_32x32x16_bf16 v[82:97], v[232:235], v[154:157], v[82:97]
	ds_read_b128 v[208:211], v252 offset:39424
	v_exp_f32_e32 v81, v81
	v_pk_add_f32 v[184:185], v[66:67], v[68:69]
	v_pk_add_f32 v[186:187], v[70:71], v[72:73]
	v_pk_add_f32 v[184:185], v[184:185], v[74:75]
	v_pk_add_f32 v[186:187], v[186:187], v[76:77]
	v_pk_add_f32 v[184:185], v[184:185], v[78:79]
	v_pk_add_f32 v[186:187], v[186:187], v[80:81]
	s_waitcnt lgkmcnt(5)
	v_mfma_f32_32x32x16_bf16 v[82:97], v[236:239], v[158:161], v[82:97]
	ds_read_b128 v[212:215], v252 offset:25632
	v_cvt_pk_bf16_f32 v66, v66, v67
	v_cvt_pk_bf16_f32 v67, v68, v69
	v_cvt_pk_bf16_f32 v68, v70, v71
	v_cvt_pk_bf16_f32 v69, v72, v73
	v_cvt_pk_bf16_f32 v70, v74, v75
	v_cvt_pk_bf16_f32 v71, v76, v77
	v_cvt_pk_bf16_f32 v72, v78, v79
	s_waitcnt lgkmcnt(5)
	v_mfma_f32_32x32x16_bf16 v[82:97], v[240:243], v[162:165], v[82:97]
	ds_read_b128 v[216:219], v252 offset:30240
	v_cvt_pk_bf16_f32 v73, v80, v81
	v_pk_add_f32 v[184:185], v[184:185], v[186:187]
	v_add_f32_e32 v184, v184, v185
	v_add_f32_e32 v182, v182, v184
	s_nop 1
	s_waitcnt lgkmcnt(5)
	v_mfma_f32_32x32x16_bf16 v[50:65], v[196:199], v[66:69], v[50:65]
	ds_read_b128 v[220:223], v252 offset:34848
	s_bitcmp1_b32 s36, 0
	s_cselect_b32 s99, 0xac00, 0
	s_add_i32 s99, s99, 0
	v_add_u32_e32 v250, s99, v170
	s_waitcnt lgkmcnt(5)
	v_mfma_f32_32x32x16_bf16 v[34:49], v[200:203], v[66:69], v[34:49]
	ds_read_b128 v[224:227], v252 offset:39456
	s_waitcnt vmcnt(4)
	ds_write_b128 v250, v[98:101]
	s_waitcnt vmcnt(3)
	ds_write_b128 v250, v[102:105] offset:12800
	s_waitcnt lgkmcnt(7)
	v_mfma_f32_32x32x16_bf16 v[18:33], v[204:207], v[66:69], v[18:33]
	ds_read_b128 v[228:231], v252 offset:25664
	v_max3_f32 v0, v82, v83, v84
	v_max3_f32 v184, v85, v86, v87
	v_max3_f32 v0, v0, v88, v89
	v_max3_f32 v184, v184, v90, v91
	v_max3_f32 v0, v0, v92, v93
	v_max3_f32 v184, v184, v94, v95
	v_max3_f32 v0, v0, v96, v97
	s_waitcnt lgkmcnt(7)
	v_mfma_f32_32x32x16_bf16 v[2:17], v[208:211], v[66:69], v[2:17]
	ds_read_b128 v[232:235], v252 offset:30272
	v_max_f32_e32 v0, v0, v184
	v_mov_b32_e32 v184, v0
	s_nop 1
	v_permlane32_swap_b32_e32 v0, v184
	v_max_f32_e32 v184, v184, v184
	v_max_f32_e32 v0, v0, v0
	v_max_f32_e32 v0, v0, v184
	s_waitcnt lgkmcnt(7)
	v_mfma_f32_32x32x16_bf16 v[50:65], v[212:215], v[70:73], v[50:65]
	ds_read_b128 v[236:239], v252 offset:34880
	v_sub_f32_e32 v184, v0, v183
	v_cmp_lt_f32_e32 vcc, s43, v184
	s_cbranch_vccnz .LaG2_R1

.LaG2_R1xb:
	s_nop 1
	s_waitcnt lgkmcnt(5)
	v_mfma_f32_32x32x16_bf16 v[50:65], v[228:231], v[74:77], v[50:65]
	ds_read_b128 v[204:207], v252 offset:34912
	v_sub_f32_e32 v90, v90, v183
	v_sub_f32_e32 v91, v91, v183
	v_sub_f32_e32 v92, v92, v183
	v_sub_f32_e32 v93, v93, v183
	v_sub_f32_e32 v94, v94, v183
	v_sub_f32_e32 v95, v95, v183
	s_waitcnt lgkmcnt(5)
	v_mfma_f32_32x32x16_bf16 v[34:49], v[232:235], v[74:77], v[34:49]
	ds_read_b128 v[208:211], v252 offset:39520
	v_sub_f32_e32 v96, v96, v183
	v_sub_f32_e32 v97, v97, v183
	v_exp_f32_e32 v90, v90
	v_exp_f32_e32 v91, v91
	v_exp_f32_e32 v92, v92
	v_exp_f32_e32 v93, v93
	s_waitcnt lgkmcnt(5)
	v_mfma_f32_32x32x16_bf16 v[18:33], v[236:239], v[74:77], v[18:33]
	v_exp_f32_e32 v94, v94
	v_exp_f32_e32 v95, v95
	v_exp_f32_e32 v96, v96
	v_exp_f32_e32 v97, v97
	v_cvt_pk_bf16_f32 v78, v90, v91
	v_cvt_pk_bf16_f32 v79, v92, v93
	s_waitcnt lgkmcnt(4)
	v_mfma_f32_32x32x16_bf16 v[2:17], v[240:243], v[74:77], v[2:17]
	v_cvt_pk_bf16_f32 v80, v94, v95
	v_cvt_pk_bf16_f32 v81, v96, v97
	v_pk_add_f32 v[184:185], v[184:185], v[90:91]
	v_pk_add_f32 v[186:187], v[186:187], v[92:93]
	v_pk_add_f32 v[184:185], v[184:185], v[94:95]
	v_pk_add_f32 v[186:187], v[186:187], v[96:97]
	s_nop 1
	s_waitcnt lgkmcnt(3)
	v_mfma_f32_32x32x16_bf16 v[50:65], v[196:199], v[78:81], v[50:65]
	v_add_u32_e32 v250, s99, v172
	s_waitcnt vmcnt(2)
	ds_write_b128 v250, v[106:109] offset:256
	s_waitcnt lgkmcnt(3)
	v_mfma_f32_32x32x16_bf16 v[34:49], v[200:203], v[78:81], v[34:49]
	v_add_u32_e32 v250, s99, v169
	s_waitcnt vmcnt(1)
	ds_write_b128 v250, v[126:129] offset:25600
	s_waitcnt lgkmcnt(3)
	v_mfma_f32_32x32x16_bf16 v[18:33], v[204:207], v[78:81], v[18:33]
	s_waitcnt vmcnt(0)
	ds_write_b128 v250, v[150:153] offset:34816
	v_pk_add_f32 v[184:185], v[184:185], v[186:187]
	s_waitcnt lgkmcnt(3)
	v_mfma_f32_32x32x16_bf16 v[2:17], v[208:211], v[78:81], v[2:17]
	v_add_f32_e32 v184, v184, v185
	v_add_f32_e32 v182, v182, v184
	s_setprio 0
	s_branch .LBB0_1490
